# attention tile loop: the 24 identity v_mov_b64 copies of the loaded-ahead tile per tile removed (on top of v018)
# speedup vs baseline: 1.0048x; 1.0048x over previous
; __device__ __forceinline__ void attn_item(const P& p, Frame& F, const bool is_s, const int b, const int g, const int c) {
;     ...
;             } else if (mode == 0) {
;                 if (i == 0) { __syncthreads(); tile_load(tr, (const bf16*)kp, (const bf16*)vp, pitch, tid); tile_store(F, tr, tid, 0); if (ntiles > 1) tile_load(tr, (const bf16*)kp + (size_t)64 * pitch, (const bf16*)vp + 128 * 64, pitch, tid); }
;                 __syncthreads();
;                 if (i + 1 < ntiles) { tile_store(F, tr, tid, ((i + 1) & 1) * A_BUF2); if (i + 2 < ntiles) tile_load(tr, (const bf16*)kp + (size_t)128 * pitch, (const bf16*)vp + 2 * 128 * 64, pitch, tid); }
.LBB0_2053:
	s_andn2_b64 vcc, exec, s[6:7]
	s_cbranch_vccnz .LBB0_2060
	s_cmp_lg_u32 s33, 0
	s_cbranch_scc1 .LBB0_2057
	v_ashrrev_i32_e32 v104, 3, v108
	v_lshlrev_b32_e32 v14, 4, v108
	v_mad_i64_i32 v[100:101], s[6:7], v104, s62, 0
	v_and_b32_e32 v2, 0x70, v14
	v_lshl_add_u64 v[4:5], v[100:101], 1, v[98:99]
	v_lshlrev_b32_e32 v2, 1, v2
	v_lshl_add_u64 v[8:9], v[4:5], 0, v[2:3]
	s_waitcnt lgkmcnt(0)
	s_barrier
	global_load_dwordx4 v[4:7], v[8:9], off offset:16
	s_nop 0
	global_load_dwordx4 v[8:11], v[8:9], off
	v_and_b32_e32 v12, 0xffffffc0, v14
	v_ashrrev_i32_e32 v13, 31, v12
	v_and_b32_e32 v14, 48, v14
	v_lshl_add_u64 v[12:13], v[12:13], 1, v[16:17]
	v_lshlrev_b32_e32 v14, 1, v14
	v_mov_b32_e32 v15, v3
	v_lshl_add_u64 v[102:103], v[12:13], 0, v[14:15]
	global_load_dwordx4 v[12:15], v[102:103], off offset:16
	global_load_dwordx4 v[194:197], v[102:103], off
	v_lshlrev_b32_e32 v105, 5, v108
	v_mul_lo_u32 v104, v104, s54
	v_and_b32_e32 v106, 0xe0, v105
	v_add3_u32 v104, 0, v104, v106
	s_movk_i32 s6, 0x88
	v_and_b32_e32 v105, 0x60, v105
	s_andn2_b64 vcc, exec, s[20:21]
	s_waitcnt vmcnt(2)
	ds_write_b128 v104, v[8:11]
	ds_write_b128 v104, v[4:7] offset:16
	v_lshrrev_b32_e32 v104, 2, v108
	v_mul_lo_u32 v104, v104, s6
	v_add3_u32 v104, 0, v104, v105
	v_add_u32_e32 v105, 0x4400, v104
	v_add_u32_e32 v104, 0x4410, v104
	s_waitcnt vmcnt(1)
	ds_write2_b64 v104, v[12:13], v[14:15] offset1:1
	s_waitcnt vmcnt(0)
	ds_write2_b64 v105, v[194:195], v[196:197] offset1:1
	s_cbranch_vccnz .LBB0_2057
	s_lshl_b32 s44, s62, 7
	v_lshl_add_u64 v[4:5], v[98:99], 0, s[44:45]
	v_lshl_add_u64 v[4:5], v[100:101], 1, v[4:5]
	s_mov_b64 s[6:7], 0x4000
	v_add_co_u32_e32 v14, vcc, 0x4000, v102
	v_lshl_add_u64 v[8:9], v[4:5], 0, v[2:3]
	v_lshl_add_u64 v[12:13], v[102:103], 0, s[6:7]
	v_addc_co_u32_e32 v15, vcc, 0, v103, vcc
	global_load_dwordx4 v[4:7], v[8:9], off offset:16
	s_nop 0
	global_load_dwordx4 v[8:11], v[8:9], off
	s_nop 0
	global_load_dwordx4 v[194:197], v[14:15], off
	s_nop 0
	global_load_dwordx4 v[12:15], v[12:13], off offset:16

; __device__ __forceinline__ void attn_item(const P& p, Frame& F, const bool is_s, const int b, const int g, const int c) {
;     ...
; #pragma nounroll
;         for (int i = 0; i < ntiles; ++i) {
;     ...
;                 if (i == 0) { __syncthreads(); tile_load(tr, (const bf16*)kp, (const bf16*)vp, pitch, tid); tile_store(F, tr, tid, 0); if (ntiles > 1) tile_load(tr, (const bf16*)kp + (size_t)64 * pitch, (const bf16*)vp + 128 * 64, pitch, tid); }
;                 __syncthreads();
;                 if (i + 1 < ntiles) { tile_store(F, tr, tid, ((i + 1) & 1) * A_BUF2); if (i + 2 < ntiles) tile_load(tr, (const bf16*)kp + (size_t)128 * pitch, (const bf16*)vp + 2 * 128 * 64, pitch, tid); }
.Lattn_m0_join:
	v_mov_b32_e32 v241, v146
	v_mov_b32_e32 v240, v243
	s_or_b64 exec, exec, s[0:1]
	s_add_i32 s33, s33, 1
	s_cmp_eq_u32 s33, s2
	s_cbranch_scc1 .LBB0_2140
.LBB0_2139:
	s_branch .LBB0_2013
.LBB0_2140:
	s_mov_b32 s62, 0xfe03f81
	s_add_i32 s5, s5, 1
	s_cmp_eq_u32 s5, 4
	s_cbranch_scc0 .LBB0_1953
